# merge loop: OG1/OG2 loads issued together with OG0 (were behind the softmax-weight division: second round trip per iteration)
# speedup vs baseline: 1.0091x; 1.0028x over previous
; __device__ __forceinline__ float bflo(unsigned u) { return __uint_as_float(u << 16); }
; __device__ __forceinline__ float bfhi(unsigned u) { return __uint_as_float(u & 0xffff0000u); }
; __device__ __forceinline__ unsigned pk2(float lo, float hi) { f32x2_t v = {lo, hi}; bf16x2_t b = __builtin_convertvector(v, bf16x2_t); return __builtin_bit_cast(unsigned, b); }
; __global__ void __launch_bounds__(NTHREADS, 2) fwd_megakernel(Args A) {
;     ...
;                 for (int i = bx * NTHREADS + tid; i < 8192 * 128; i += G * NTHREADS) {
;                     const int row = i >> 7, o8 = i & 127, h = o8 >> 3;
;                     const float l0 = LSE[((size_t)0 * 8192 + row) * 16 + h], l1 = LSE[((size_t)1 * 8192 + row) * 16 + h], l2 = LSE[((size_t)2 * 8192 + row) * 16 + h];
;                     const float mx = fmaxf(l0, fmaxf(l1, l2)); const float e0 = __expf(l0 - mx), e1 = __expf(l1 - mx), e2 = __expf(l2 - mx); const float inv = 1.f / (e0 + e1 + e2);
;                     const float w0 = e0 * inv, w1 = e1 * inv, w2 = e2 * inv;
;                     const size_t off = (size_t)row * DM + 8 * o8;
;                     const v4u a = *(const v4u*)(OG0 + off), b = *(const v4u*)(OG1 + off), c = *(const v4u*)(OG2 + off);
;                     v4u o;
;                     o.x = pk2(w0 * bflo(a.x) + w1 * bflo(b.x) + w2 * bflo(c.x), w0 * bfhi(a.x) + w1 * bfhi(b.x) + w2 * bfhi(c.x));
;                     o.y = pk2(w0 * bflo(a.y) + w1 * bflo(b.y) + w2 * bflo(c.y), w0 * bfhi(a.y) + w1 * bfhi(b.y) + w2 * bfhi(c.y));
;                     o.z = pk2(w0 * bflo(a.z) + w1 * bflo(b.z) + w2 * bflo(c.z), w0 * bfhi(a.z) + w1 * bfhi(b.z) + w2 * bfhi(c.z));
;                     o.w = pk2(w0 * bflo(a.w) + w1 * bflo(b.w) + w2 * bflo(c.w), w0 * bfhi(a.w) + w1 * bfhi(b.w) + w2 * bfhi(c.w));
;                     *(v4u*)(Y + (size_t)row_base * DM + off) = o;
;                 }
.LBB0_403:
	s_waitcnt vmcnt(3)
	v_ashrrev_i32_e32 v4, 7, v1
	v_ashrrev_i32_e32 v5, 31, v4
	v_lshlrev_b64 v[2:3], 6, v[4:5]
	v_lshl_add_u64 v[2:3], s[6:7], 0, v[2:3]
	v_mov_b32_e32 v147, v0
	v_lshl_add_u64 v[2:3], v[2:3], 0, v[146:147]
	v_add_co_u32_e32 v6, vcc, 0x80000, v2
	global_load_dword v8, v[2:3], off
	s_nop 0
	v_addc_co_u32_e32 v7, vcc, 0, v3, vcc
	global_load_dword v6, v[6:7], off
	v_add_co_u32_e32 v2, vcc, s21, v2
	v_lshlrev_b64 v[20:21], 11, v[4:5]
	s_nop 0
	v_addc_co_u32_e32 v3, vcc, 0, v3, vcc
	global_load_dword v2, v[2:3], off
	v_lshl_or_b32 v20, v144, 1, v20
	s_waitcnt vmcnt(5)
	v_lshl_add_u64 v[12:13], s[24:25], 0, v[20:21]
	global_load_dwordx4 v[12:15], v[12:13], off
	v_lshl_add_u64 v[4:5], s[80:81], 0, v[20:21]
	v_lshl_add_u64 v[26:27], s[8:9], 0, v[20:21]
	global_load_dwordx4 v[30:33], v[4:5], off
	global_load_dwordx4 v[34:37], v[26:27], off
	v_add_u32_e32 v1, s20, v1
	s_waitcnt vmcnt(3)
	v_max3_f32 v3, v8, v6, v2
	v_sub_f32_e32 v7, v8, v3
	v_sub_f32_e32 v6, v6, v3
	v_mul_f32_e32 v7, 0x3fb8aa3b, v7
	v_mul_f32_e32 v6, 0x3fb8aa3b, v6
	v_sub_f32_e32 v2, v2, v3
	v_exp_f32_e32 v17, v7
	v_exp_f32_e32 v16, v6
	v_mul_f32_e32 v2, 0x3fb8aa3b, v2
	v_exp_f32_e32 v2, v2
	s_waitcnt vmcnt(2)
	v_lshlrev_b32_e32 v24, 16, v12
	v_add_f32_e32 v3, v17, v16
	v_and_b32_e32 v25, 0xffff0000, v12
	v_add_f32_e32 v3, v2, v3
	v_div_scale_f32 v6, s[4:5], v3, v3, 1.0
	v_rcp_f32_e32 v7, v6
	v_lshlrev_b32_e32 v12, 16, v13
	v_and_b32_e32 v13, 0xffff0000, v13
	s_mov_b32 s4, 0xfffff
	v_fma_f32 v8, -v6, v7, 1.0
	v_fmac_f32_e32 v7, v8, v7
	v_div_scale_f32 v8, vcc, 1.0, v3, 1.0
	v_mul_f32_e32 v9, v8, v7
	v_fma_f32 v10, -v6, v9, v8
	v_fmac_f32_e32 v9, v10, v7
	v_fma_f32 v6, -v6, v9, v8
	v_div_fmas_f32 v6, v6, v7, v9
	v_div_fixup_f32 v18, v6, v3, 1.0
	v_pk_mul_f32 v[16:17], v[16:17], v[18:19] op_sel_hi:[1,0]
	v_mul_f32_e32 v2, v2, v18
	v_cmp_lt_i32_e32 vcc, s4, v1
	s_or_b64 s[2:3], vcc, s[2:3]
	s_waitcnt vmcnt(1)
	v_lshlrev_b32_e32 v22, 16, v30
	v_and_b32_e32 v19, 0xffff0000, v30
	s_waitcnt vmcnt(0)
	v_and_b32_e32 v23, 0xffff0000, v34
	v_lshlrev_b32_e32 v18, 16, v34
	v_pk_mul_f32 v[22:23], v[16:17], v[22:23] op_sel:[1,0] op_sel_hi:[0,1]
	v_pk_fma_f32 v[18:19], v[16:17], v[18:19], v[22:23]
	v_lshlrev_b32_e32 v34, 16, v31
	v_pk_fma_f32 v[18:19], v[2:3], v[24:25], v[18:19] op_sel_hi:[0,1,1]
	v_cvt_pk_bf16_f32 v30, v18, v19
	v_lshlrev_b32_e32 v18, 16, v35
	v_and_b32_e32 v35, 0xffff0000, v35
	v_and_b32_e32 v19, 0xffff0000, v31
	v_pk_mul_f32 v[34:35], v[16:17], v[34:35] op_sel:[1,0] op_sel_hi:[0,1]
	v_pk_fma_f32 v[34:35], v[16:17], v[18:19], v[34:35]
	v_lshlrev_b32_e32 v18, 16, v14
	v_pk_fma_f32 v[34:35], v[2:3], v[12:13], v[34:35] op_sel_hi:[0,1,1]
	v_lshlrev_b32_e32 v12, 16, v32
	v_and_b32_e32 v13, 0xffff0000, v36
	v_cvt_pk_bf16_f32 v31, v34, v35
	v_lshlrev_b32_e32 v34, 16, v36
	v_and_b32_e32 v35, 0xffff0000, v32
	v_pk_mul_f32 v[12:13], v[16:17], v[12:13] op_sel:[1,0] op_sel_hi:[0,1]
	v_and_b32_e32 v19, 0xffff0000, v14
	v_pk_fma_f32 v[34:35], v[16:17], v[34:35], v[12:13]
	v_lshlrev_b32_e32 v36, 16, v33
	v_pk_fma_f32 v[34:35], v[2:3], v[18:19], v[34:35] op_sel_hi:[0,1,1]
	v_cvt_pk_bf16_f32 v32, v34, v35
	v_lshlrev_b32_e32 v34, 16, v37
	v_and_b32_e32 v37, 0xffff0000, v37
	v_and_b32_e32 v35, 0xffff0000, v33
	v_pk_mul_f32 v[36:37], v[16:17], v[36:37] op_sel:[1,0] op_sel_hi:[0,1]
	v_pk_fma_f32 v[34:35], v[16:17], v[34:35], v[36:37]
	v_lshlrev_b32_e32 v36, 16, v15
	v_and_b32_e32 v37, 0xffff0000, v15
	v_pk_fma_f32 v[2:3], v[2:3], v[36:37], v[34:35] op_sel_hi:[0,1,1]
	v_cvt_pk_bf16_f32 v33, v2, v3
	v_lshl_add_u64 v[2:3], s[28:29], 0, v[20:21]
	global_store_dwordx4 v[2:3], v[30:33], off
	s_andn2_b64 exec, exec, s[2:3]
	s_cbranch_execnz .LBB0_403
